# attn loop: scale rows with the previous max speculatively (fmamk interleaved with the row-max chain); the rare max-update path re-bases the 16 already-scaled values
# speedup vs baseline: 1.0037x; 1.0037x over previous
; __device__ __forceinline__ void finishSM(f32x16& p0, f32x16& p1, float alpha, float& l_reg, bf16x8& pa0, bf16x8& pa1, bf16x8& pa2, bf16x8& pa3) {
; #pragma unroll
;   for (int r = 0; r < 16; ++r) p1[r] = __builtin_amdgcn_exp2f(p1[r]);
;   float ps = 0;
; #pragma unroll
;   for (int r = 0; r < 16; ++r) ps += p0[r];
; #pragma unroll
;   for (int r = 0; r < 16; ++r) ps += p1[r];
;   { auto rr = __builtin_amdgcn_permlane32_swap(__float_as_uint(ps), __float_as_uint(ps), false, false);
;     ps = __uint_as_float(rr[0]) + __uint_as_float(rr[1]); }
;   l_reg = l_reg * alpha + ps;
;     ...
;   PK4(p0, 0, pa0); PK4(p0, 8, pa1); PK4(p1, 0, pa2); PK4(p1, 8, pa3);
;     ...
; }
; __device__ __forceinline__ void qkt(f32x16& p0, f32x16& p1, const char* Ks, const bf16x8* qr, const char* qrl, int r32, int hi) {
;   p0 = f32x16{}; p1 = f32x16{};
; #pragma unroll
;   for (int d0 = 0; d0 < 8; ++d0) { int cb = (d0 * 16 + hi * 8) * 2;
;     bf16x8 b0 = *reinterpret_cast<const bf16x8*>(Ks + KSWZ(r32, cb));
;     bf16x8 b1 = *reinterpret_cast<const bf16x8*>(Ks + KSWZ(32 + r32, cb));
;     p0 = __builtin_amdgcn_mfma_f32_32x32x16_bf16(b0, qr[d0], p0, 0, 0, 0);
;     p1 = __builtin_amdgcn_mfma_f32_32x32x16_bf16(b1, qr[d0], p1, 0, 0, 0); }
; #pragma unroll
;   for (int d0 = 8; d0 < 12; ++d0) { int cb = (d0 * 16 + hi * 8) * 2;
;     bf16x8 b0 = *reinterpret_cast<const bf16x8*>(Ks + KSWZ(r32, cb));
;     bf16x8 b1 = *reinterpret_cast<const bf16x8*>(Ks + KSWZ(32 + r32, cb));
;     bf16x8 qf = *reinterpret_cast<const bf16x8*>(qrl + (((2 * (d0 - 8) + hi) ^ ((r32 >> 1) & 7)) << 4));
;     p0 = __builtin_amdgcn_mfma_f32_32x32x16_bf16(b0, qf, p0, 0, 0, 0);
;     p1 = __builtin_amdgcn_mfma_f32_32x32x16_bf16(b1, qf, p1, 0, 0, 0); }
; }
.LBB0_1151:
	s_sub_i32 s30, s76, 1
	s_cmp_eq_u32 s76, 0
	s_cselect_b32 s30, 2, s30
	s_add_i32 s18, s76, 1
	s_cmp_lg_u32 s76, 2
	s_cselect_b32 s18, s18, 0
	ds_read_b128 v[232:235], v199 offset:36864
	ds_read_b128 v[236:239], v199 offset:49152
	ds_read_b128 v[240:243], v205 offset:36864
	ds_read_b128 v[248:251], v205 offset:49152
	ds_read_b128 v[244:247], v206 offset:36864
	v_exp_f32_e32 v162, v162
	v_add_f32_e32 v211, v225, v228
	v_exp_f32_e32 v163, v163
	v_add_f32_e32 v211, v226, v211
	v_exp_f32_e32 v160, v160
	s_waitcnt lgkmcnt(3)
	v_mfma_f32_32x32x16_bf16 v[80:95], v[232:235], v[124:127], 0
	ds_read_b128 v[232:235], v206 offset:49152
	v_add_f32_e32 v211, v229, v211
	v_exp_f32_e32 v161, v161
	v_add_f32_e32 v211, v227, v211
	v_exp_f32_e32 v158, v158
	v_mfma_f32_32x32x16_bf16 v[64:79], v[236:239], v[124:127], 0
	ds_read_b128 v[236:239], v208 offset:36864
	v_add_f32_e32 v211, v230, v211
	v_exp_f32_e32 v159, v159
	v_add_f32_e32 v211, v223, v211
	v_exp_f32_e32 v156, v156
	s_waitcnt lgkmcnt(3)
	v_mfma_f32_32x32x16_bf16 v[80:95], v[240:243], v[120:123], v[80:95]
	ds_read_b128 v[240:243], v208 offset:49152
	v_add_f32_e32 v211, v224, v211
	v_exp_f32_e32 v157, v157
	v_add_f32_e32 v211, v219, v211
	v_exp_f32_e32 v154, v154
	v_mfma_f32_32x32x16_bf16 v[64:79], v[248:251], v[120:123], v[64:79]
	ds_read_b128 v[248:251], v207 offset:36864
	v_add_f32_e32 v211, v221, v211
	v_exp_f32_e32 v155, v155
	v_add_f32_e32 v211, v220, v211
	v_exp_f32_e32 v152, v152
	s_waitcnt lgkmcnt(3)
	v_mfma_f32_32x32x16_bf16 v[80:95], v[244:247], v[116:119], v[80:95]
	ds_read_b128 v[244:247], v207 offset:49152
	v_add_f32_e32 v211, v222, v211
	v_exp_f32_e32 v153, v153
	v_add_f32_e32 v211, v215, v211
	v_exp_f32_e32 v150, v150
	v_mfma_f32_32x32x16_bf16 v[64:79], v[232:235], v[116:119], v[64:79]
	ds_read_b128 v[232:235], v204 offset:36864
	v_add_f32_e32 v211, v217, v211
	v_exp_f32_e32 v151, v151
	v_add_f32_e32 v211, v216, v211
	v_exp_f32_e32 v148, v148
	s_waitcnt lgkmcnt(3)
	v_mfma_f32_32x32x16_bf16 v[80:95], v[236:239], v[112:115], v[80:95]
	ds_read_b128 v[236:239], v204 offset:49152
	v_add_f32_e32 v211, v218, v211
	v_exp_f32_e32 v149, v149
	v_add_f32_e32 v212, v162, v163
	v_add_f32_e32 v212, v160, v212
	v_add_f32_e32 v212, v161, v212
	v_mfma_f32_32x32x16_bf16 v[64:79], v[240:243], v[112:115], v[64:79]
	ds_read_b128 v[240:243], v203 offset:36864
	v_add_f32_e32 v212, v158, v212
	v_add_f32_e32 v212, v159, v212
	v_add_f32_e32 v212, v156, v212
	v_add_f32_e32 v212, v157, v212
	v_add_f32_e32 v212, v154, v212
	v_add_f32_e32 v212, v155, v212
	s_waitcnt lgkmcnt(3)
	v_mfma_f32_32x32x16_bf16 v[80:95], v[248:251], v[108:111], v[80:95]
	ds_read_b128 v[248:251], v203 offset:49152
	v_add_f32_e32 v212, v152, v212
	v_add_f32_e32 v212, v153, v212
	v_add_f32_e32 v212, v150, v212
	v_add_f32_e32 v212, v151, v212
	v_add_f32_e32 v212, v148, v212
	v_add_f32_e32 v212, v149, v212
	v_mfma_f32_32x32x16_bf16 v[64:79], v[244:247], v[108:111], v[64:79]
	ds_read_b128 v[244:247], v200 offset:36864
	v_add_f32_e32 v211, v211, v212
	v_mov_b32_e32 v212, v211
	s_lshl_b32 s19, s18, 14
	v_add_u32_e32 v231, s19, v183
	s_waitcnt vmcnt(0)
	ds_write_b128 v231, v[140:143]
	v_add_u32_e32 v140, s19, v184
	ds_write_b128 v140, v[144:147]
	ds_write_b128 v185, v[136:139] offset:12288
	s_waitcnt lgkmcnt(6)
	v_mfma_f32_32x32x16_bf16 v[80:95], v[232:235], v[104:107], v[80:95]
	ds_read_b128 v[232:235], v200 offset:49152
	ds_write_b128 v185, v[132:135] offset:24576
	s_mov_b32 s18, 0xfffa0000
	ds_write_b128 v186, v[128:131] offset:12288
	v_add_co_u32_e32 v128, vcc, s18, v168
	s_mov_b32 s18, 0xfffc0000
	s_nop 0
	v_addc_co_u32_e32 v129, vcc, -1, v169, vcc
	v_add_co_u32_e32 v130, vcc, s18, v168
	s_movk_i32 s18, 0xe000
	s_nop 0
	v_addc_co_u32_e32 v131, vcc, -1, v169, vcc
	v_mfma_f32_32x32x16_bf16 v[64:79], v[236:239], v[104:107], v[64:79]
	ds_read_b128 v[236:239], v191 offset:36864
	global_load_dwordx4 v[140:143], v[128:129], off
	global_load_dwordx4 v[136:139], v[128:129], off offset:-256
	global_load_dwordx4 v[144:147], v[130:131], off
	global_load_dwordx4 v[132:135], v[130:131], off offset:-256
	v_add_co_u32_e32 v128, vcc, s18, v166
	s_nop 1
	v_addc_co_u32_e32 v129, vcc, -1, v167, vcc
	s_waitcnt lgkmcnt(8)
	v_mfma_f32_32x32x16_bf16 v[80:95], v[240:243], v[100:103], v[80:95]
	ds_read_b128 v[240:243], v202 offset:49152
	global_load_dwordx4 v[128:131], v[128:129], off
	v_cvt_pk_bf16_f32 v158, v158, v159
	v_cvt_pk_bf16_f32 v159, v156, v157
	v_permlane32_swap_b32_e32 v211, v212
	v_cvt_pk_bf16_f32 v156, v162, v163
	v_cvt_pk_bf16_f32 v157, v160, v161
	v_mfma_f32_32x32x16_bf16 v[64:79], v[248:251], v[100:103], v[64:79]
	ds_read_b128 v[248:251], v182
	v_cvt_pk_bf16_f32 v160, v154, v155
	v_cvt_pk_bf16_f32 v161, v152, v153
	v_cvt_pk_bf16_f32 v162, v150, v151
	v_cvt_pk_bf16_f32 v163, v148, v149
	v_add_f32_e32 v211, v211, v212
	v_cvt_pk_bf16_f32 v148, v225, v228
	s_waitcnt lgkmcnt(5)
	v_mfma_f32_32x32x16_bf16 v[80:95], v[244:247], v[96:99], v[80:95]
	ds_read_b128 v[244:247], v198 offset:36864
	v_cvt_pk_bf16_f32 v149, v226, v229
	v_cvt_pk_bf16_f32 v150, v227, v230
	v_cvt_pk_bf16_f32 v151, v223, v224
	v_cvt_pk_bf16_f32 v152, v219, v221
	v_cvt_pk_bf16_f32 v153, v220, v222
	v_cvt_pk_bf16_f32 v154, v215, v217
	v_mfma_f32_32x32x16_bf16 v[64:79], v[232:235], v[96:99], v[64:79]
	ds_read_b128 v[232:235], v201 offset:49152
	v_cvt_pk_bf16_f32 v155, v216, v218
	v_fma_f32 v176, v209, v176, v211
	s_waitcnt lgkmcnt(2)
; #define SBAR() __builtin_amdgcn_sched_barrier(0)
; __device__ __forceinline__ void partialSM(f32x16& p0, f32x16& p1, float& m_reg, float& mn, float& alpha) {
;   constexpr float C = SCALE * 1.4426950408889634f;
;   float pmax = p0[0];
; #pragma unroll
;   for (int r = 1; r < 16; ++r) pmax = fmaxf(pmax, p0[r]);
; #pragma unroll
;   for (int r = 0; r < 16; ++r) pmax = fmaxf(pmax, p1[r]);
;   { auto rr = __builtin_amdgcn_permlane32_swap(__float_as_uint(pmax), __float_as_uint(pmax), false, false);
;     pmax = fmaxf(__uint_as_float(rr[0]), __uint_as_float(rr[1])); }
;   if (__builtin_expect(__all(pmax - m_reg <= THR / SCALE), 1)) { mn = m_reg; alpha = 1.f; }
;   else { mn = fmaxf(m_reg, pmax); alpha = __builtin_amdgcn_exp2f((m_reg - mn) * C); m_reg = mn; }
;   float mnC = -mn * C;
; #pragma unroll
;   for (int r = 0; r < 16; ++r) p0[r] = fmaf(p0[r], C, mnC);
; #pragma unroll
;   for (int r = 0; r < 16; ++r) p1[r] = fmaf(p1[r], C, mnC);
; #pragma unroll
;   for (int r = 0; r < 16; ++r) p0[r] = __builtin_amdgcn_exp2f(p0[r]);
; }
; template <int OFF> __device__ __forceinline__ s16x4 tr_read(int vb) {
;   s16x4 r; asm volatile("ds_read_b64_tr_b16 %0, %1 offset:%2" : "=&v"(r) : "v"(vb), "i"(OFF) : "memory"); return r;
; }
; template <int D0> __device__ __forceinline__ void pv_one(f32x16& od, int vb, bf16x8 pa0, bf16x8 pa1, bf16x8 pa2, bf16x8 pa3) {
;   const s16x4 l0 = tr_read<v_rd_off(D0, 0, 0)>(vb), h0 = tr_read<v_rd_off(D0, 0, 1)>(vb), l1 = tr_read<v_rd_off(D0, 1, 0)>(vb), h1 = tr_read<v_rd_off(D0, 1, 1)>(vb);
;   const s16x4 l2 = tr_read<v_rd_off(D0, 2, 0)>(vb), h2 = tr_read<v_rd_off(D0, 2, 1)>(vb), l3 = tr_read<v_rd_off(D0, 3, 0)>(vb), h3 = tr_read<v_rd_off(D0, 3, 1)>(vb);
;   asm volatile("s_waitcnt lgkmcnt(0)" ::: "memory"); SBAR();
;     ...
;   od = __builtin_amdgcn_mfma_f32_32x32x16_bf16(pa0, PK(l0, h0), od, 0, 0, 0);
;   od = __builtin_amdgcn_mfma_f32_32x32x16_bf16(pa1, PK(l1, h1), od, 0, 0, 0);
;   od = __builtin_amdgcn_mfma_f32_32x32x16_bf16(pa2, PK(l2, h2), od, 0, 0, 0);
;   od = __builtin_amdgcn_mfma_f32_32x32x16_bf16(pa3, PK(l3, h3), od, 0, 0, 0);
;     ...
; }
; __device__ __forceinline__ void pv_d0(f32x16* o, int vb, bf16x8 pa0, bf16x8 pa1, bf16x8 pa2, bf16x8 pa3) {
;   pv_one<0>(o[0], vb, pa0, pa1, pa2, pa3); pv_one<1>(o[1], vb, pa0, pa1, pa2, pa3); pv_one<2>(o[2], vb, pa0, pa1, pa2, pa3); pv_one<3>(o[3], vb, pa0, pa1, pa2, pa3);
	v_mfma_f32_32x32x16_bf16 v[80:95], v[236:239], v[248:251], v[80:95]
	ds_read_b128 v[236:239], v181
	v_mfma_f32_32x32x16_bf16 v[64:79], v[240:243], v[248:251], v[64:79]
	ds_read_b128 v[240:243], v187 offset:36864
	ds_read_b128 v[248:251], v189 offset:49152
	s_waitcnt lgkmcnt(2)
	v_mfma_f32_32x32x16_bf16 v[80:95], v[244:247], v[236:239], v[80:95]
	ds_read_b128 v[244:247], v179
	v_mfma_f32_32x32x16_bf16 v[64:79], v[232:235], v[236:239], v[64:79]
	ds_read_b128 v[232:235], v188 offset:36864
	ds_read_b128 v[236:239], v190 offset:49152
	s_waitcnt lgkmcnt(2)
	v_mfma_f32_32x32x16_bf16 v[80:95], v[240:243], v[244:247], v[80:95]
	ds_read_b128 v[240:243], v177
	v_mfma_f32_32x32x16_bf16 v[64:79], v[248:251], v[244:247], v[64:79]
	s_waitcnt lgkmcnt(0)
	v_mfma_f32_32x32x16_bf16 v[80:95], v[232:235], v[240:243], v[80:95]
	v_mfma_f32_32x32x16_bf16 v[64:79], v[236:239], v[240:243], v[64:79]
	s_lshl_b32 s31, s30, 14
	v_add_u32_e32 v180, s31, v178
	ds_read_b64_tr_b16 v[232:233], v180 offset:0
	ds_read_b64_tr_b16 v[234:235], v180 offset:2048
	ds_read_b64_tr_b16 v[236:237], v180 offset:512
	ds_read_b64_tr_b16 v[238:239], v180 offset:2560
	ds_read_b64_tr_b16 v[240:241], v180 offset:1024
	ds_read_b64_tr_b16 v[242:243], v180 offset:3072
	ds_read_b64_tr_b16 v[248:249], v180 offset:1536
	ds_read_b64_tr_b16 v[250:251], v180 offset:3584
	ds_read_b64_tr_b16 v[244:245], v180 offset:4096
	ds_read_b64_tr_b16 v[246:247], v180 offset:6144
	s_nop 3
	v_mul_f32_e32 v212, 0xbdd53b94, v210
	v_max3_f32 v194, v80, v81, v82
	v_fmamk_f32 v225, v80, 0x3dd53b94, v212
	v_max3_f32 v195, v64, v65, v66
	v_fmamk_f32 v228, v81, 0x3dd53b94, v212
	s_waitcnt lgkmcnt(6)
	v_mfma_f32_32x32x16_bf16 v[32:47], v[148:151], v[232:235], v[32:47]
	ds_read_b64_tr_b16 v[232:233], v180 offset:4608
	ds_read_b64_tr_b16 v[234:235], v180 offset:6656
	v_max3_f32 v194, v194, v83, v84
	v_fmamk_f32 v226, v82, 0x3dd53b94, v212
	v_max3_f32 v195, v195, v67, v68
	v_fmamk_f32 v229, v83, 0x3dd53b94, v212
	v_max3_f32 v194, v194, v85, v86
	v_mfma_f32_32x32x16_bf16 v[48:63], v[148:151], v[236:239], v[48:63]
	ds_read_b64_tr_b16 v[236:237], v180 offset:5120
	ds_read_b64_tr_b16 v[238:239], v180 offset:7168
	v_fmamk_f32 v227, v84, 0x3dd53b94, v212
	v_max3_f32 v195, v195, v69, v70
	v_fmamk_f32 v230, v85, 0x3dd53b94, v212
	v_max3_f32 v194, v194, v87, v88
	v_fmamk_f32 v223, v86, 0x3dd53b94, v212
	s_waitcnt lgkmcnt(6)
	v_mfma_f32_32x32x16_bf16 v[16:31], v[148:151], v[240:243], v[16:31]
	ds_read_b64_tr_b16 v[240:241], v180 offset:5632
	ds_read_b64_tr_b16 v[242:243], v180 offset:7680
	v_max3_f32 v195, v195, v71, v72
	v_fmamk_f32 v224, v87, 0x3dd53b94, v212
	v_max3_f32 v194, v194, v89, v90
	v_fmamk_f32 v219, v88, 0x3dd53b94, v212
	v_max3_f32 v195, v195, v73, v74
	v_mfma_f32_32x32x16_bf16 v[0:15], v[148:151], v[248:251], v[0:15]
	ds_read_b64_tr_b16 v[248:249], v180 offset:8192
	ds_read_b64_tr_b16 v[250:251], v180 offset:10240
	v_fmamk_f32 v221, v89, 0x3dd53b94, v212
	v_max3_f32 v194, v194, v91, v92
	v_fmamk_f32 v220, v90, 0x3dd53b94, v212
	v_max3_f32 v195, v195, v75, v76
	v_fmamk_f32 v222, v91, 0x3dd53b94, v212
	s_waitcnt lgkmcnt(6)
	v_mfma_f32_32x32x16_bf16 v[32:47], v[152:155], v[244:247], v[32:47]
	ds_read_b64_tr_b16 v[244:245], v180 offset:8704
	ds_read_b64_tr_b16 v[246:247], v180 offset:10752
	v_max3_f32 v194, v194, v93, v94
	v_fmamk_f32 v215, v92, 0x3dd53b94, v212
	v_max3_f32 v195, v195, v77, v78
	v_fmamk_f32 v217, v93, 0x3dd53b94, v212
	v_max3_f32 v194, v194, v95, v195
	v_mfma_f32_32x32x16_bf16 v[48:63], v[152:155], v[232:235], v[48:63]
	ds_read_b64_tr_b16 v[232:233], v180 offset:9216
	ds_read_b64_tr_b16 v[234:235], v180 offset:11264
	v_fmamk_f32 v216, v94, 0x3dd53b94, v212
	v_max_f32_e32 v194, v194, v79
	v_fmamk_f32 v218, v95, 0x3dd53b94, v212
	v_mov_b32_e32 v195, v194
	s_nop 1
	s_waitcnt lgkmcnt(6)
	v_mfma_f32_32x32x16_bf16 v[16:31], v[152:155], v[236:239], v[16:31]
	ds_read_b64_tr_b16 v[236:237], v180 offset:9728
	ds_read_b64_tr_b16 v[238:239], v180 offset:11776
	v_permlane32_swap_b32_e32 v194, v195
	v_max_f32_e32 v194, v194, v195
	v_sub_f32_e32 v195, v194, v210
	v_cmp_ge_f32_e32 vcc, s15, v195
	v_mfma_f32_32x32x16_bf16 v[0:15], v[152:155], v[240:243], v[0:15]
	ds_read_b64_tr_b16 v[240:241], v180 offset:12288
	ds_read_b64_tr_b16 v[242:243], v180 offset:14336
	s_cmp_eq_u64 vcc, exec
	s_cselect_b64 s[40:41], -1, 0
	s_cbranch_scc1 .Lattn_fast1p
	v_max_f32_e32 v194, v210, v194
	v_sub_f32_e32 v195, v210, v194
	v_mul_f32_e32 v195, 0x3dd53b94, v195
	v_exp_f32_e32 v214, v195
	v_mov_b32_e32 v210, v194
	v_mul_f32_e32 v212, 0xbdd53b94, v194
	v_add_f32_e32 v225, v225, v195
	v_add_f32_e32 v228, v228, v195
	v_add_f32_e32 v226, v226, v195
	v_add_f32_e32 v229, v229, v195
	v_add_f32_e32 v227, v227, v195
	v_add_f32_e32 v230, v230, v195
	v_add_f32_e32 v223, v223, v195
	v_add_f32_e32 v224, v224, v195
	v_add_f32_e32 v219, v219, v195
	v_add_f32_e32 v221, v221, v195
	v_add_f32_e32 v220, v220, v195
	v_add_f32_e32 v222, v222, v195
	v_add_f32_e32 v215, v215, v195
	v_add_f32_e32 v217, v217, v195
	v_add_f32_e32 v216, v216, v195
	v_add_f32_e32 v218, v218, v195
	s_branch .Lattn_join1p

; #define SBAR() __builtin_amdgcn_sched_barrier(0)
; template <int OFF> __device__ __forceinline__ s16x4 tr_read(int vb) {
;   s16x4 r; asm volatile("ds_read_b64_tr_b16 %0, %1 offset:%2" : "=&v"(r) : "v"(vb), "i"(OFF) : "memory"); return r;
; }
; template <int D0> __device__ __forceinline__ void pv_one(f32x16& od, int vb, bf16x8 pa0, bf16x8 pa1, bf16x8 pa2, bf16x8 pa3) {
;   const s16x4 l0 = tr_read<v_rd_off(D0, 0, 0)>(vb), h0 = tr_read<v_rd_off(D0, 0, 1)>(vb), l1 = tr_read<v_rd_off(D0, 1, 0)>(vb), h1 = tr_read<v_rd_off(D0, 1, 1)>(vb);
;   const s16x4 l2 = tr_read<v_rd_off(D0, 2, 0)>(vb), h2 = tr_read<v_rd_off(D0, 2, 1)>(vb), l3 = tr_read<v_rd_off(D0, 3, 0)>(vb), h3 = tr_read<v_rd_off(D0, 3, 1)>(vb);
;   asm volatile("s_waitcnt lgkmcnt(0)" ::: "memory"); SBAR();
;     ...
;   od = __builtin_amdgcn_mfma_f32_32x32x16_bf16(pa0, PK(l0, h0), od, 0, 0, 0);
;   od = __builtin_amdgcn_mfma_f32_32x32x16_bf16(pa1, PK(l1, h1), od, 0, 0, 0);
;   od = __builtin_amdgcn_mfma_f32_32x32x16_bf16(pa2, PK(l2, h2), od, 0, 0, 0);
;   od = __builtin_amdgcn_mfma_f32_32x32x16_bf16(pa3, PK(l3, h3), od, 0, 0, 0);
;     ...
; }
; __device__ __forceinline__ void pv_d0(f32x16* o, int vb, bf16x8 pa0, bf16x8 pa1, bf16x8 pa2, bf16x8 pa3) {
;   pv_one<0>(o[0], vb, pa0, pa1, pa2, pa3); pv_one<1>(o[1], vb, pa0, pa1, pa2, pa3); pv_one<2>(o[2], vb, pa0, pa1, pa2, pa3); pv_one<3>(o[3], vb, pa0, pa1, pa2, pa3);
.Lattn_join1p:
	v_fmamk_f32 v150, v76, 0x3dd53b94, v212
	v_fmamk_f32 v151, v77, 0x3dd53b94, v212
	s_waitcnt lgkmcnt(6)
	v_mfma_f32_32x32x16_bf16 v[32:47], v[156:159], v[248:251], v[32:47]
	ds_read_b64_tr_b16 v[248:249], v180 offset:12800
	ds_read_b64_tr_b16 v[250:251], v180 offset:14848
	v_fmamk_f32 v148, v78, 0x3dd53b94, v212
	v_fmamk_f32 v149, v79, 0x3dd53b94, v212
	v_fmamk_f32 v154, v72, 0x3dd53b94, v212
	v_fmamk_f32 v155, v73, 0x3dd53b94, v212
	v_fmamk_f32 v152, v74, 0x3dd53b94, v212
	v_mfma_f32_32x32x16_bf16 v[48:63], v[156:159], v[244:247], v[48:63]
	ds_read_b64_tr_b16 v[244:245], v180 offset:13312
	ds_read_b64_tr_b16 v[246:247], v180 offset:15360
	v_fmamk_f32 v153, v75, 0x3dd53b94, v212
	s_waitcnt lgkmcnt(6)
	v_mfma_f32_32x32x16_bf16 v[16:31], v[156:159], v[232:235], v[16:31]
	ds_read_b64_tr_b16 v[232:233], v180 offset:13824
	ds_read_b64_tr_b16 v[234:235], v180 offset:15872
	v_mfma_f32_32x32x16_bf16 v[0:15], v[156:159], v[236:239], v[0:15]
	v_fmamk_f32 v158, v68, 0x3dd53b94, v212
	v_fmamk_f32 v159, v69, 0x3dd53b94, v212
	v_fmamk_f32 v156, v70, 0x3dd53b94, v212
	v_fmamk_f32 v157, v71, 0x3dd53b94, v212
	s_waitcnt lgkmcnt(0)
	s_barrier
	ds_read_b128 v[236:239], v199 offset:12288
	v_mfma_f32_32x32x16_bf16 v[32:47], v[160:163], v[240:243], v[32:47]
	ds_read_b128 v[240:243], v199 offset:24576
	v_mfma_f32_32x32x16_bf16 v[48:63], v[160:163], v[248:251], v[48:63]
	ds_read_b128 v[248:251], v205 offset:12288
	v_mfma_f32_32x32x16_bf16 v[16:31], v[160:163], v[244:247], v[16:31]
	ds_read_b128 v[244:247], v205 offset:24576
	v_mfma_f32_32x32x16_bf16 v[0:15], v[160:163], v[232:235], v[0:15]
	ds_read_b128 v[232:235], v206 offset:12288
	v_fmamk_f32 v162, v64, 0x3dd53b94, v212
	v_fmamk_f32 v163, v65, 0x3dd53b94, v212
	v_fmamk_f32 v160, v66, 0x3dd53b94, v212
	v_fmamk_f32 v161, v67, 0x3dd53b94, v212
	s_and_b64 vcc, exec, s[40:41]
	s_cbranch_vccnz .Lattn_skip_rs1p
	s_and_saveexec_b64 s[18:19], s[38:39]
	ds_write_b32 v175, v214 offset:128
	s_or_b64 exec, exec, s[18:19]
	s_waitcnt lgkmcnt(0)
	v_add_u32_e32 v194, v173, v164
	ds_read_b128 v[64:67], v194 offset:224
	ds_read_b128 v[68:71], v194 offset:192
	ds_read_b128 v[72:75], v194 offset:160
	ds_read_b128 v[76:79], v194 offset:128
	s_waitcnt lgkmcnt(0)
	v_pk_mul_f32 v[44:45], v[44:45], v[64:65]
	v_pk_mul_f32 v[46:47], v[46:47], v[66:67]
	v_pk_mul_f32 v[40:41], v[40:41], v[68:69]
	v_pk_mul_f32 v[42:43], v[42:43], v[70:71]
	v_pk_mul_f32 v[36:37], v[36:37], v[72:73]
	v_pk_mul_f32 v[38:39], v[38:39], v[74:75]
	v_pk_mul_f32 v[32:33], v[32:33], v[76:77]
	v_pk_mul_f32 v[34:35], v[34:35], v[78:79]
	v_pk_mul_f32 v[60:61], v[60:61], v[64:65]
	v_pk_mul_f32 v[62:63], v[62:63], v[66:67]
	v_pk_mul_f32 v[56:57], v[56:57], v[68:69]
	v_pk_mul_f32 v[58:59], v[58:59], v[70:71]
	v_pk_mul_f32 v[52:53], v[52:53], v[72:73]
	v_pk_mul_f32 v[54:55], v[54:55], v[74:75]
	v_pk_mul_f32 v[48:49], v[48:49], v[76:77]
	v_pk_mul_f32 v[50:51], v[50:51], v[78:79]
	v_pk_mul_f32 v[28:29], v[28:29], v[64:65]
	v_pk_mul_f32 v[30:31], v[30:31], v[66:67]
	v_pk_mul_f32 v[24:25], v[24:25], v[68:69]
	v_pk_mul_f32 v[26:27], v[26:27], v[70:71]
	v_pk_mul_f32 v[20:21], v[20:21], v[72:73]
	v_pk_mul_f32 v[22:23], v[22:23], v[74:75]
	v_pk_mul_f32 v[16:17], v[16:17], v[76:77]
	v_pk_mul_f32 v[18:19], v[18:19], v[78:79]
	v_pk_mul_f32 v[12:13], v[12:13], v[64:65]
	v_pk_mul_f32 v[14:15], v[14:15], v[66:67]
	v_pk_mul_f32 v[8:9], v[8:9], v[68:69]
	v_pk_mul_f32 v[10:11], v[10:11], v[70:71]
	v_pk_mul_f32 v[4:5], v[4:5], v[72:73]
	v_pk_mul_f32 v[6:7], v[6:7], v[74:75]
	v_pk_mul_f32 v[0:1], v[0:1], v[76:77]
	v_pk_mul_f32 v[2:3], v[2:3], v[78:79]

; __device__ __forceinline__ void partialSM(f32x16& p0, f32x16& p1, float& m_reg, float& mn, float& alpha) {
;   constexpr float C = SCALE * 1.4426950408889634f;
;   float pmax = p0[0];
; #pragma unroll
;   for (int r = 1; r < 16; ++r) pmax = fmaxf(pmax, p0[r]);
; #pragma unroll
;   for (int r = 0; r < 16; ++r) pmax = fmaxf(pmax, p1[r]);
;   { auto rr = __builtin_amdgcn_permlane32_swap(__float_as_uint(pmax), __float_as_uint(pmax), false, false);
;     pmax = fmaxf(__uint_as_float(rr[0]), __uint_as_float(rr[1])); }
;   if (__builtin_expect(__all(pmax - m_reg <= THR / SCALE), 1)) { mn = m_reg; alpha = 1.f; }
;   else { mn = fmaxf(m_reg, pmax); alpha = __builtin_amdgcn_exp2f((m_reg - mn) * C); m_reg = mn; }
;   float mnC = -mn * C;
; #pragma unroll
;   for (int r = 0; r < 16; ++r) p0[r] = fmaf(p0[r], C, mnC);
; #pragma unroll
;   for (int r = 0; r < 16; ++r) p1[r] = fmaf(p1[r], C, mnC);
; #pragma unroll
;   for (int r = 0; r < 16; ++r) p0[r] = __builtin_amdgcn_exp2f(p0[r]);
; }
; __device__ __forceinline__ void finishSM(f32x16& p0, f32x16& p1, float alpha, float& l_reg, bf16x8& pa0, bf16x8& pa1, bf16x8& pa2, bf16x8& pa3) {
; #pragma unroll
;   for (int r = 0; r < 16; ++r) p1[r] = __builtin_amdgcn_exp2f(p1[r]);
;   float ps = 0;
; #pragma unroll
;   for (int r = 0; r < 16; ++r) ps += p0[r];
; #pragma unroll
;   for (int r = 0; r < 16; ++r) ps += p1[r];
;   { auto rr = __builtin_amdgcn_permlane32_swap(__float_as_uint(ps), __float_as_uint(ps), false, false);
;     ps = __uint_as_float(rr[0]) + __uint_as_float(rr[1]); }
;   l_reg = l_reg * alpha + ps;
;     ...
;   PK4(p0, 0, pa0); PK4(p0, 8, pa1); PK4(p1, 0, pa2); PK4(p1, 8, pa3);
;     ...
; }
; template <int OFF> __device__ __forceinline__ s16x4 tr_read(int vb) {
;   s16x4 r; asm volatile("ds_read_b64_tr_b16 %0, %1 offset:%2" : "=&v"(r) : "v"(vb), "i"(OFF) : "memory"); return r;
; }
; template <int D0> __device__ __forceinline__ void pv_one(f32x16& od, int vb, bf16x8 pa0, bf16x8 pa1, bf16x8 pa2, bf16x8 pa3) {
;   const s16x4 l0 = tr_read<v_rd_off(D0, 0, 0)>(vb), h0 = tr_read<v_rd_off(D0, 0, 1)>(vb), l1 = tr_read<v_rd_off(D0, 1, 0)>(vb), h1 = tr_read<v_rd_off(D0, 1, 1)>(vb);
;   const s16x4 l2 = tr_read<v_rd_off(D0, 2, 0)>(vb), h2 = tr_read<v_rd_off(D0, 2, 1)>(vb), l3 = tr_read<v_rd_off(D0, 3, 0)>(vb), h3 = tr_read<v_rd_off(D0, 3, 1)>(vb);
;   asm volatile("s_waitcnt lgkmcnt(0)" ::: "memory"); SBAR();
.Lattn_noloadp:
	s_waitcnt lgkmcnt(3)
	v_mfma_f32_32x32x16_bf16 v[80:95], v[232:235], v[240:243], v[80:95]
	ds_read_b128 v[232:235], v179
	v_cvt_pk_bf16_f32 v158, v158, v159
	v_cvt_pk_bf16_f32 v159, v156, v157
	v_permlane32_swap_b32_e32 v211, v212
	v_cvt_pk_bf16_f32 v156, v162, v163
	v_cvt_pk_bf16_f32 v157, v160, v161
	v_cvt_pk_bf16_f32 v160, v154, v155
	v_mfma_f32_32x32x16_bf16 v[64:79], v[236:239], v[240:243], v[64:79]
	ds_read_b128 v[236:239], v188 offset:12288
	ds_read_b128 v[240:243], v190 offset:24576
	v_cvt_pk_bf16_f32 v161, v152, v153
	v_cvt_pk_bf16_f32 v162, v150, v151
	v_cvt_pk_bf16_f32 v163, v148, v149
	v_add_f32_e32 v211, v211, v212
	v_cvt_pk_bf16_f32 v148, v225, v228
	v_cvt_pk_bf16_f32 v149, v226, v229
	s_waitcnt lgkmcnt(2)
	v_mfma_f32_32x32x16_bf16 v[80:95], v[248:251], v[232:235], v[80:95]
	ds_read_b128 v[248:251], v177
	v_cvt_pk_bf16_f32 v150, v227, v230
	v_cvt_pk_bf16_f32 v151, v223, v224
	v_cvt_pk_bf16_f32 v152, v219, v221
	v_cvt_pk_bf16_f32 v153, v220, v222
	v_cvt_pk_bf16_f32 v154, v215, v217
	v_cvt_pk_bf16_f32 v155, v216, v218
	v_mfma_f32_32x32x16_bf16 v[64:79], v[244:247], v[232:235], v[64:79]
	v_fma_f32 v176, v214, v176, v211
	s_waitcnt lgkmcnt(0)
	v_mfma_f32_32x32x16_bf16 v[80:95], v[236:239], v[248:251], v[80:95]
	v_mfma_f32_32x32x16_bf16 v[64:79], v[240:243], v[248:251], v[64:79]
	v_lshl_add_u32 v231, s76, 14, v178
	ds_read_b64_tr_b16 v[232:233], v231 offset:0
	ds_read_b64_tr_b16 v[234:235], v231 offset:2048
	ds_read_b64_tr_b16 v[236:237], v231 offset:512
	ds_read_b64_tr_b16 v[238:239], v231 offset:2560
	ds_read_b64_tr_b16 v[240:241], v231 offset:1024
	ds_read_b64_tr_b16 v[242:243], v231 offset:3072
	ds_read_b64_tr_b16 v[248:249], v231 offset:1536
	ds_read_b64_tr_b16 v[250:251], v231 offset:3584
	ds_read_b64_tr_b16 v[244:245], v231 offset:4096
	ds_read_b64_tr_b16 v[246:247], v231 offset:6144
	s_nop 3
	s_mov_b64 s[100:101], 0x4000
	v_lshl_add_u64 v[166:167], v[166:167], 0, s[100:101]
	v_lshl_add_u64 v[168:169], v[168:169], 0, s[10:11]
	v_mul_f32_e32 v212, 0xbdd53b94, v210
	v_max3_f32 v194, v80, v81, v82
	v_fmamk_f32 v225, v80, 0x3dd53b94, v212
	s_waitcnt lgkmcnt(6)
	v_mfma_f32_32x32x16_bf16 v[32:47], v[148:151], v[232:235], v[32:47]
	ds_read_b64_tr_b16 v[232:233], v231 offset:4608
	ds_read_b64_tr_b16 v[234:235], v231 offset:6656
	v_max3_f32 v195, v64, v65, v66
	v_fmamk_f32 v228, v81, 0x3dd53b94, v212
	v_max3_f32 v194, v194, v83, v84
	v_fmamk_f32 v226, v82, 0x3dd53b94, v212
	v_max3_f32 v195, v195, v67, v68
	v_mfma_f32_32x32x16_bf16 v[48:63], v[148:151], v[236:239], v[48:63]
	ds_read_b64_tr_b16 v[236:237], v231 offset:5120
	ds_read_b64_tr_b16 v[238:239], v231 offset:7168
	v_fmamk_f32 v229, v83, 0x3dd53b94, v212
	v_max3_f32 v194, v194, v85, v86
	v_fmamk_f32 v227, v84, 0x3dd53b94, v212
	v_max3_f32 v195, v195, v69, v70
	v_fmamk_f32 v230, v85, 0x3dd53b94, v212
	s_waitcnt lgkmcnt(6)
	v_mfma_f32_32x32x16_bf16 v[16:31], v[148:151], v[240:243], v[16:31]
	ds_read_b64_tr_b16 v[240:241], v231 offset:5632
	ds_read_b64_tr_b16 v[242:243], v231 offset:7680
	v_max3_f32 v194, v194, v87, v88
	v_fmamk_f32 v223, v86, 0x3dd53b94, v212
	v_max3_f32 v195, v195, v71, v72
	v_fmamk_f32 v224, v87, 0x3dd53b94, v212
	v_max3_f32 v194, v194, v89, v90
	v_mfma_f32_32x32x16_bf16 v[0:15], v[148:151], v[248:251], v[0:15]
	ds_read_b64_tr_b16 v[248:249], v231 offset:8192
	ds_read_b64_tr_b16 v[250:251], v231 offset:10240
	v_fmamk_f32 v219, v88, 0x3dd53b94, v212
	v_max3_f32 v195, v195, v73, v74
	v_fmamk_f32 v221, v89, 0x3dd53b94, v212
	v_max3_f32 v194, v194, v91, v92
	v_fmamk_f32 v220, v90, 0x3dd53b94, v212
	s_waitcnt lgkmcnt(6)
	v_mfma_f32_32x32x16_bf16 v[32:47], v[152:155], v[244:247], v[32:47]
	ds_read_b64_tr_b16 v[244:245], v231 offset:8704
	ds_read_b64_tr_b16 v[246:247], v231 offset:10752
	v_max3_f32 v195, v195, v75, v76
	v_fmamk_f32 v222, v91, 0x3dd53b94, v212
	v_max3_f32 v194, v194, v93, v94
	v_fmamk_f32 v215, v92, 0x3dd53b94, v212
	v_max3_f32 v195, v195, v77, v78
	v_mfma_f32_32x32x16_bf16 v[48:63], v[152:155], v[232:235], v[48:63]
	ds_read_b64_tr_b16 v[232:233], v231 offset:9216
	ds_read_b64_tr_b16 v[234:235], v231 offset:11264
	v_fmamk_f32 v217, v93, 0x3dd53b94, v212
	v_max3_f32 v194, v194, v95, v195
	v_fmamk_f32 v216, v94, 0x3dd53b94, v212
	v_max_f32_e32 v194, v194, v79
	v_fmamk_f32 v218, v95, 0x3dd53b94, v212
	s_waitcnt lgkmcnt(6)
	v_mfma_f32_32x32x16_bf16 v[16:31], v[152:155], v[236:239], v[16:31]
	ds_read_b64_tr_b16 v[236:237], v231 offset:9728
	ds_read_b64_tr_b16 v[238:239], v231 offset:11776
	v_mov_b32_e32 v195, v194
	s_nop 1
	v_permlane32_swap_b32_e32 v194, v195
	v_max_f32_e32 v194, v194, v195
	v_sub_f32_e32 v195, v194, v210
	v_mfma_f32_32x32x16_bf16 v[0:15], v[152:155], v[240:243], v[0:15]
	ds_read_b64_tr_b16 v[240:241], v231 offset:12288
	ds_read_b64_tr_b16 v[242:243], v231 offset:14336
	v_cmp_ge_f32_e32 vcc, s15, v195
	s_cmp_eq_u64 vcc, exec
	s_cselect_b64 s[40:41], -1, 0
	s_cbranch_scc1 .Lattn_fast2p
	v_max_f32_e32 v194, v210, v194
	v_sub_f32_e32 v195, v210, v194
	v_mul_f32_e32 v195, 0x3dd53b94, v195
	v_exp_f32_e32 v213, v195
	v_mov_b32_e32 v210, v194
	v_mul_f32_e32 v212, 0xbdd53b94, v194
	v_add_f32_e32 v225, v225, v195
	v_add_f32_e32 v228, v228, v195
	v_add_f32_e32 v226, v226, v195
	v_add_f32_e32 v229, v229, v195
	v_add_f32_e32 v227, v227, v195
	v_add_f32_e32 v230, v230, v195
	v_add_f32_e32 v223, v223, v195
	v_add_f32_e32 v224, v224, v195
	v_add_f32_e32 v219, v219, v195
	v_add_f32_e32 v221, v221, v195
	v_add_f32_e32 v220, v220, v195
	v_add_f32_e32 v222, v222, v195
	v_add_f32_e32 v215, v215, v195
	v_add_f32_e32 v217, v217, v195
	v_add_f32_e32 v216, v216, v195
	v_add_f32_e32 v218, v218, v195
	s_branch .Lattn_join2p

; #define SBAR() __builtin_amdgcn_sched_barrier(0)
; template <int OFF> __device__ __forceinline__ s16x4 tr_read(int vb) {
;   s16x4 r; asm volatile("ds_read_b64_tr_b16 %0, %1 offset:%2" : "=&v"(r) : "v"(vb), "i"(OFF) : "memory"); return r;
; }
; template <int D0> __device__ __forceinline__ void pv_one(f32x16& od, int vb, bf16x8 pa0, bf16x8 pa1, bf16x8 pa2, bf16x8 pa3) {
;   const s16x4 l0 = tr_read<v_rd_off(D0, 0, 0)>(vb), h0 = tr_read<v_rd_off(D0, 0, 1)>(vb), l1 = tr_read<v_rd_off(D0, 1, 0)>(vb), h1 = tr_read<v_rd_off(D0, 1, 1)>(vb);
;   const s16x4 l2 = tr_read<v_rd_off(D0, 2, 0)>(vb), h2 = tr_read<v_rd_off(D0, 2, 1)>(vb), l3 = tr_read<v_rd_off(D0, 3, 0)>(vb), h3 = tr_read<v_rd_off(D0, 3, 1)>(vb);
;   asm volatile("s_waitcnt lgkmcnt(0)" ::: "memory"); SBAR();
;     ...
;   od = __builtin_amdgcn_mfma_f32_32x32x16_bf16(pa0, PK(l0, h0), od, 0, 0, 0);
;   od = __builtin_amdgcn_mfma_f32_32x32x16_bf16(pa1, PK(l1, h1), od, 0, 0, 0);
;   od = __builtin_amdgcn_mfma_f32_32x32x16_bf16(pa2, PK(l2, h2), od, 0, 0, 0);
;   od = __builtin_amdgcn_mfma_f32_32x32x16_bf16(pa3, PK(l3, h3), od, 0, 0, 0);
;     ...
; }
; __device__ __forceinline__ void pv_d0(f32x16* o, int vb, bf16x8 pa0, bf16x8 pa1, bf16x8 pa2, bf16x8 pa3) {
;   pv_one<0>(o[0], vb, pa0, pa1, pa2, pa3); pv_one<1>(o[1], vb, pa0, pa1, pa2, pa3); pv_one<2>(o[2], vb, pa0, pa1, pa2, pa3); pv_one<3>(o[3], vb, pa0, pa1, pa2, pa3);
.Lattn_join2p:
	s_sub_i32 s100, s30, 1
	s_cmp_eq_u32 s30, 0
	s_cselect_b32 s100, 2, s100
	s_add_i32 s101, s30, 1
	s_cmp_lg_u32 s30, 2
	s_cselect_b32 s101, s101, 0
	s_movk_i32 s34, 0x6000
	s_waitcnt lgkmcnt(6)
	v_mfma_f32_32x32x16_bf16 v[32:47], v[156:159], v[248:251], v[32:47]
	ds_read_b64_tr_b16 v[248:249], v231 offset:12800
	ds_read_b64_tr_b16 v[250:251], v231 offset:14848
	v_fmamk_f32 v150, v76, 0x3dd53b94, v212
	v_fmamk_f32 v151, v77, 0x3dd53b94, v212
	v_fmamk_f32 v148, v78, 0x3dd53b94, v212
	v_fmamk_f32 v149, v79, 0x3dd53b94, v212
	v_fmamk_f32 v154, v72, 0x3dd53b94, v212
	v_mfma_f32_32x32x16_bf16 v[48:63], v[156:159], v[244:247], v[48:63]
	ds_read_b64_tr_b16 v[244:245], v231 offset:13312
	ds_read_b64_tr_b16 v[246:247], v231 offset:15360
	v_fmamk_f32 v155, v73, 0x3dd53b94, v212
	v_fmamk_f32 v152, v74, 0x3dd53b94, v212
	v_fmamk_f32 v153, v75, 0x3dd53b94, v212
	s_waitcnt lgkmcnt(6)
	v_mfma_f32_32x32x16_bf16 v[16:31], v[156:159], v[232:235], v[16:31]
	ds_read_b64_tr_b16 v[232:233], v231 offset:13824
	ds_read_b64_tr_b16 v[234:235], v231 offset:15872
	v_mfma_f32_32x32x16_bf16 v[0:15], v[156:159], v[236:239], v[0:15]
	v_fmamk_f32 v158, v68, 0x3dd53b94, v212
	v_fmamk_f32 v159, v69, 0x3dd53b94, v212
	v_fmamk_f32 v156, v70, 0x3dd53b94, v212
	v_fmamk_f32 v157, v71, 0x3dd53b94, v212
	s_waitcnt lgkmcnt(0)
	s_barrier
	ds_read_b128 v[236:239], v199 offset:36864
	v_mfma_f32_32x32x16_bf16 v[32:47], v[160:163], v[240:243], v[32:47]
	ds_read_b128 v[240:243], v199 offset:49152
	v_mfma_f32_32x32x16_bf16 v[48:63], v[160:163], v[248:251], v[48:63]
	ds_read_b128 v[248:251], v205 offset:36864
	v_mfma_f32_32x32x16_bf16 v[16:31], v[160:163], v[244:247], v[16:31]
	ds_read_b128 v[244:247], v205 offset:49152
	v_mfma_f32_32x32x16_bf16 v[0:15], v[160:163], v[232:235], v[0:15]
	ds_read_b128 v[232:235], v206 offset:36864
	v_fmamk_f32 v162, v64, 0x3dd53b94, v212
	v_fmamk_f32 v163, v65, 0x3dd53b94, v212
	v_fmamk_f32 v160, v66, 0x3dd53b94, v212
	v_fmamk_f32 v161, v67, 0x3dd53b94, v212
	s_and_b64 vcc, exec, s[40:41]
	s_cbranch_vccnz .Lattn_skip_rs2p
	s_and_saveexec_b64 s[18:19], s[38:39]
	ds_write_b32 v175, v213 offset:128
	s_or_b64 exec, exec, s[18:19]
	s_waitcnt lgkmcnt(0)
	v_add_u32_e32 v194, v173, v164
	ds_read_b128 v[64:67], v194 offset:224
	ds_read_b128 v[68:71], v194 offset:192
	ds_read_b128 v[72:75], v194 offset:160
	ds_read_b128 v[76:79], v194 offset:128
	s_waitcnt lgkmcnt(0)
	v_pk_mul_f32 v[44:45], v[44:45], v[64:65]
	v_pk_mul_f32 v[46:47], v[46:47], v[66:67]
	v_pk_mul_f32 v[40:41], v[40:41], v[68:69]
	v_pk_mul_f32 v[42:43], v[42:43], v[70:71]
	v_pk_mul_f32 v[36:37], v[36:37], v[72:73]
	v_pk_mul_f32 v[38:39], v[38:39], v[74:75]
	v_pk_mul_f32 v[32:33], v[32:33], v[76:77]
	v_pk_mul_f32 v[34:35], v[34:35], v[78:79]
	v_pk_mul_f32 v[60:61], v[60:61], v[64:65]
	v_pk_mul_f32 v[62:63], v[62:63], v[66:67]
	v_pk_mul_f32 v[56:57], v[56:57], v[68:69]
	v_pk_mul_f32 v[58:59], v[58:59], v[70:71]
	v_pk_mul_f32 v[52:53], v[52:53], v[72:73]
	v_pk_mul_f32 v[54:55], v[54:55], v[74:75]
	v_pk_mul_f32 v[48:49], v[48:49], v[76:77]
	v_pk_mul_f32 v[50:51], v[50:51], v[78:79]
	v_pk_mul_f32 v[28:29], v[28:29], v[64:65]
	v_pk_mul_f32 v[30:31], v[30:31], v[66:67]
	v_pk_mul_f32 v[24:25], v[24:25], v[68:69]
	v_pk_mul_f32 v[26:27], v[26:27], v[70:71]
	v_pk_mul_f32 v[20:21], v[20:21], v[72:73]
	v_pk_mul_f32 v[22:23], v[22:23], v[74:75]
	v_pk_mul_f32 v[16:17], v[16:17], v[76:77]
	v_pk_mul_f32 v[18:19], v[18:19], v[78:79]
	v_pk_mul_f32 v[12:13], v[12:13], v[64:65]
	v_pk_mul_f32 v[14:15], v[14:15], v[66:67]
	v_pk_mul_f32 v[8:9], v[8:9], v[68:69]
	v_pk_mul_f32 v[10:11], v[10:11], v[70:71]
	v_pk_mul_f32 v[4:5], v[4:5], v[72:73]
	v_pk_mul_f32 v[6:7], v[6:7], v[74:75]
	v_pk_mul_f32 v[0:1], v[0:1], v[76:77]
	v_pk_mul_f32 v[2:3], v[2:3], v[78:79]

; __device__ __forceinline__ void finishSM(f32x16& p0, f32x16& p1, float alpha, float& l_reg, bf16x8& pa0, bf16x8& pa1, bf16x8& pa2, bf16x8& pa3) {
; #pragma unroll
;   for (int r = 0; r < 16; ++r) p1[r] = __builtin_amdgcn_exp2f(p1[r]);
;   float ps = 0;
; #pragma unroll
;   for (int r = 0; r < 16; ++r) ps += p0[r];
; #pragma unroll
;   for (int r = 0; r < 16; ++r) ps += p1[r];
;   { auto rr = __builtin_amdgcn_permlane32_swap(__float_as_uint(ps), __float_as_uint(ps), false, false);
;     ps = __uint_as_float(rr[0]) + __uint_as_float(rr[1]); }
;   l_reg = l_reg * alpha + ps;
;     ...
;   PK4(p0, 0, pa0); PK4(p0, 8, pa1); PK4(p1, 0, pa2); PK4(p1, 8, pa3);
;     ...
; }
; __device__ __forceinline__ void qkt(f32x16& p0, f32x16& p1, const char* Ks, const bf16x8* qr, const char* qrl, int r32, int hi) {
;   p0 = f32x16{}; p1 = f32x16{};
; #pragma unroll
;   for (int d0 = 0; d0 < 8; ++d0) { int cb = (d0 * 16 + hi * 8) * 2;
;     bf16x8 b0 = *reinterpret_cast<const bf16x8*>(Ks + KSWZ(r32, cb));
;     bf16x8 b1 = *reinterpret_cast<const bf16x8*>(Ks + KSWZ(32 + r32, cb));
;     p0 = __builtin_amdgcn_mfma_f32_32x32x16_bf16(b0, qr[d0], p0, 0, 0, 0);
;     p1 = __builtin_amdgcn_mfma_f32_32x32x16_bf16(b1, qr[d0], p1, 0, 0, 0); }
; #pragma unroll
;   for (int d0 = 8; d0 < 12; ++d0) { int cb = (d0 * 16 + hi * 8) * 2;
;     bf16x8 b0 = *reinterpret_cast<const bf16x8*>(Ks + KSWZ(r32, cb));
;     bf16x8 b1 = *reinterpret_cast<const bf16x8*>(Ks + KSWZ(32 + r32, cb));
;     bf16x8 qf = *reinterpret_cast<const bf16x8*>(qrl + (((2 * (d0 - 8) + hi) ^ ((r32 >> 1) & 7)) << 4));
;     p0 = __builtin_amdgcn_mfma_f32_32x32x16_bf16(b0, qf, p0, 0, 0, 0);
;     p1 = __builtin_amdgcn_mfma_f32_32x32x16_bf16(b1, qf, p1, 0, 0, 0); }
; }
.Lattn_steady:
	v_exp_f32_e32 v225, v225
	v_exp_f32_e32 v228, v228
	v_exp_f32_e32 v226, v226
	v_add_f32_e32 v211, v225, v228
	s_waitcnt lgkmcnt(3)
	v_mfma_f32_32x32x16_bf16 v[80:95], v[236:239], v[124:127], 0
	ds_read_b128 v[236:239], v206 offset:49152
	v_exp_f32_e32 v229, v229
	v_add_f32_e32 v211, v226, v211
	v_exp_f32_e32 v227, v227
	v_add_f32_e32 v211, v229, v211
	v_mfma_f32_32x32x16_bf16 v[64:79], v[240:243], v[124:127], 0
	ds_read_b128 v[240:243], v208 offset:36864
	v_exp_f32_e32 v230, v230
	v_add_f32_e32 v211, v227, v211
	v_exp_f32_e32 v223, v223
	v_add_f32_e32 v211, v230, v211
	s_waitcnt lgkmcnt(3)
	v_mfma_f32_32x32x16_bf16 v[80:95], v[248:251], v[120:123], v[80:95]
	ds_read_b128 v[248:251], v208 offset:49152
	v_exp_f32_e32 v224, v224
	v_add_f32_e32 v211, v223, v211
	v_exp_f32_e32 v219, v219
	v_add_f32_e32 v211, v224, v211
	v_mfma_f32_32x32x16_bf16 v[64:79], v[244:247], v[120:123], v[64:79]
	ds_read_b128 v[244:247], v207 offset:36864
	v_exp_f32_e32 v221, v221
	v_add_f32_e32 v211, v219, v211
	v_exp_f32_e32 v220, v220
	v_add_f32_e32 v211, v221, v211
	s_waitcnt lgkmcnt(3)
	v_mfma_f32_32x32x16_bf16 v[80:95], v[232:235], v[116:119], v[80:95]
	ds_read_b128 v[232:235], v207 offset:49152
	v_exp_f32_e32 v222, v222
	v_add_f32_e32 v211, v220, v211
	v_exp_f32_e32 v215, v215
	v_add_f32_e32 v211, v222, v211
	v_mfma_f32_32x32x16_bf16 v[64:79], v[236:239], v[116:119], v[64:79]
	ds_read_b128 v[236:239], v204 offset:36864
	v_exp_f32_e32 v217, v217
	v_add_f32_e32 v211, v215, v211
	v_exp_f32_e32 v216, v216
	v_add_f32_e32 v211, v217, v211
	s_waitcnt lgkmcnt(3)
	v_mfma_f32_32x32x16_bf16 v[80:95], v[240:243], v[112:115], v[80:95]
	ds_read_b128 v[240:243], v204 offset:49152
	v_exp_f32_e32 v218, v218
	v_add_f32_e32 v211, v216, v211
	v_exp_f32_e32 v162, v162
	v_add_f32_e32 v211, v218, v211
	v_mfma_f32_32x32x16_bf16 v[64:79], v[248:251], v[112:115], v[64:79]
	ds_read_b128 v[248:251], v203 offset:36864
	v_exp_f32_e32 v163, v163
	v_exp_f32_e32 v160, v160
	v_exp_f32_e32 v161, v161
	s_waitcnt lgkmcnt(3)
	v_mfma_f32_32x32x16_bf16 v[80:95], v[244:247], v[108:111], v[80:95]
	ds_read_b128 v[244:247], v203 offset:49152
	v_exp_f32_e32 v158, v158
	v_exp_f32_e32 v159, v159
	v_exp_f32_e32 v156, v156
	v_mfma_f32_32x32x16_bf16 v[64:79], v[232:235], v[108:111], v[64:79]
	ds_read_b128 v[232:235], v200 offset:36864
	v_exp_f32_e32 v157, v157
	v_exp_f32_e32 v154, v154
	v_exp_f32_e32 v155, v155
	s_waitcnt lgkmcnt(3)
	v_mfma_f32_32x32x16_bf16 v[80:95], v[236:239], v[104:107], v[80:95]
	ds_read_b128 v[236:239], v200 offset:49152
	v_exp_f32_e32 v152, v152
	v_exp_f32_e32 v153, v153
	v_exp_f32_e32 v150, v150
	v_mfma_f32_32x32x16_bf16 v[64:79], v[240:243], v[104:107], v[64:79]
	ds_read_b128 v[240:243], v191 offset:36864
	v_exp_f32_e32 v151, v151
	v_exp_f32_e32 v148, v148
	v_exp_f32_e32 v149, v149
	s_waitcnt lgkmcnt(3)
	v_mfma_f32_32x32x16_bf16 v[80:95], v[248:251], v[100:103], v[80:95]
	ds_read_b128 v[248:251], v202 offset:49152
	v_add_f32_e32 v212, v162, v163
	v_add_f32_e32 v212, v160, v212
	v_add_f32_e32 v212, v161, v212
	v_add_f32_e32 v212, v158, v212
	v_add_f32_e32 v212, v159, v212
	v_add_f32_e32 v212, v156, v212
	v_mfma_f32_32x32x16_bf16 v[64:79], v[244:247], v[100:103], v[64:79]
	ds_read_b128 v[244:247], v182
	v_add_f32_e32 v212, v157, v212
	v_add_f32_e32 v212, v154, v212
	v_add_f32_e32 v212, v155, v212
	v_add_f32_e32 v212, v152, v212
	v_add_f32_e32 v212, v153, v212
	v_add_f32_e32 v212, v150, v212
	s_waitcnt lgkmcnt(3)
	v_mfma_f32_32x32x16_bf16 v[80:95], v[232:235], v[96:99], v[80:95]
	ds_read_b128 v[232:235], v198 offset:36864
	v_add_f32_e32 v212, v151, v212
	v_add_f32_e32 v212, v148, v212
	v_add_f32_e32 v212, v149, v212
	v_add_f32_e32 v211, v211, v212
	v_mov_b32_e32 v212, v211
	s_lshl_b32 s19, s18, 14
	v_add_u32_e32 v231, s19, v183
	s_waitcnt vmcnt(0)
	v_mfma_f32_32x32x16_bf16 v[64:79], v[236:239], v[96:99], v[64:79]
	ds_read_b128 v[236:239], v201 offset:49152
	ds_write_b128 v231, v[140:143]
	v_add_u32_e32 v140, s19, v184
	ds_write_b128 v140, v[144:147]
	ds_write_b128 v185, v[136:139] offset:12288
	ds_write_b128 v185, v[132:135] offset:24576
	s_mov_b32 s18, 0xfffa0000
	ds_write_b128 v186, v[128:131] offset:12288
	v_add_co_u32_e32 v128, vcc, s18, v168
	s_mov_b32 s18, 0xfffc0000
	s_nop 0
	s_waitcnt lgkmcnt(7)
	v_mfma_f32_32x32x16_bf16 v[80:95], v[240:243], v[244:247], v[80:95]
	ds_read_b128 v[240:243], v181
	v_addc_co_u32_e32 v129, vcc, -1, v169, vcc
	v_add_co_u32_e32 v130, vcc, s18, v168
	s_movk_i32 s18, 0xe000
	s_nop 0
	v_addc_co_u32_e32 v131, vcc, -1, v169, vcc
	global_load_dwordx4 v[140:143], v[128:129], off
	global_load_dwordx4 v[136:139], v[128:129], off offset:-256
	global_load_dwordx4 v[144:147], v[130:131], off
	v_mfma_f32_32x32x16_bf16 v[64:79], v[248:251], v[244:247], v[64:79]
	ds_read_b128 v[248:251], v187 offset:36864
	ds_read_b128 v[244:247], v189 offset:49152
	global_load_dwordx4 v[132:135], v[130:131], off offset:-256
	v_add_co_u32_e32 v128, vcc, s18, v166
	s_nop 1
	v_addc_co_u32_e32 v129, vcc, -1, v167, vcc
	global_load_dwordx4 v[128:131], v[128:129], off
	v_cvt_pk_bf16_f32 v158, v158, v159
	v_cvt_pk_bf16_f32 v159, v156, v157
	s_waitcnt lgkmcnt(2)
; __device__ __forceinline__ void partialSM(f32x16& p0, f32x16& p1, float& m_reg, float& mn, float& alpha) {
;   constexpr float C = SCALE * 1.4426950408889634f;
;   float pmax = p0[0];
; #pragma unroll
;   for (int r = 1; r < 16; ++r) pmax = fmaxf(pmax, p0[r]);
; #pragma unroll
;   for (int r = 0; r < 16; ++r) pmax = fmaxf(pmax, p1[r]);
;   { auto rr = __builtin_amdgcn_permlane32_swap(__float_as_uint(pmax), __float_as_uint(pmax), false, false);
;     pmax = fmaxf(__uint_as_float(rr[0]), __uint_as_float(rr[1])); }
;   if (__builtin_expect(__all(pmax - m_reg <= THR / SCALE), 1)) { mn = m_reg; alpha = 1.f; }
;   else { mn = fmaxf(m_reg, pmax); alpha = __builtin_amdgcn_exp2f((m_reg - mn) * C); m_reg = mn; }
;   float mnC = -mn * C;
; #pragma unroll
;   for (int r = 0; r < 16; ++r) p0[r] = fmaf(p0[r], C, mnC);
; #pragma unroll
;   for (int r = 0; r < 16; ++r) p1[r] = fmaf(p1[r], C, mnC);
; #pragma unroll
;   for (int r = 0; r < 16; ++r) p0[r] = __builtin_amdgcn_exp2f(p0[r]);
; }
; __device__ __forceinline__ void finishSM(f32x16& p0, f32x16& p1, float alpha, float& l_reg, bf16x8& pa0, bf16x8& pa1, bf16x8& pa2, bf16x8& pa3) {
; #pragma unroll
;   for (int r = 0; r < 16; ++r) p1[r] = __builtin_amdgcn_exp2f(p1[r]);
;   float ps = 0;
; #pragma unroll
;   for (int r = 0; r < 16; ++r) ps += p0[r];
; #pragma unroll
;   for (int r = 0; r < 16; ++r) ps += p1[r];
;   { auto rr = __builtin_amdgcn_permlane32_swap(__float_as_uint(ps), __float_as_uint(ps), false, false);
;     ps = __uint_as_float(rr[0]) + __uint_as_float(rr[1]); }
;   l_reg = l_reg * alpha + ps;
;     ...
;   PK4(p0, 0, pa0); PK4(p0, 8, pa1); PK4(p1, 0, pa2); PK4(p1, 8, pa3);
;     ...
; }
; template <int OFF> __device__ __forceinline__ s16x4 tr_read(int vb) {
;   s16x4 r; asm volatile("ds_read_b64_tr_b16 %0, %1 offset:%2" : "=&v"(r) : "v"(vb), "i"(OFF) : "memory"); return r;
; }
; template <int D0> __device__ __forceinline__ void pv_one(f32x16& od, int vb, bf16x8 pa0, bf16x8 pa1, bf16x8 pa2, bf16x8 pa3) {
;   const s16x4 l0 = tr_read<v_rd_off(D0, 0, 0)>(vb), h0 = tr_read<v_rd_off(D0, 0, 1)>(vb), l1 = tr_read<v_rd_off(D0, 1, 0)>(vb), h1 = tr_read<v_rd_off(D0, 1, 1)>(vb);
;   const s16x4 l2 = tr_read<v_rd_off(D0, 2, 0)>(vb), h2 = tr_read<v_rd_off(D0, 2, 1)>(vb), l3 = tr_read<v_rd_off(D0, 3, 0)>(vb), h3 = tr_read<v_rd_off(D0, 3, 1)>(vb);
;   asm volatile("s_waitcnt lgkmcnt(0)" ::: "memory"); SBAR();
	v_mfma_f32_32x32x16_bf16 v[80:95], v[232:235], v[240:243], v[80:95]
	ds_read_b128 v[232:235], v179
	v_permlane32_swap_b32_e32 v211, v212
	v_cvt_pk_bf16_f32 v156, v162, v163
	v_cvt_pk_bf16_f32 v157, v160, v161
	v_cvt_pk_bf16_f32 v160, v154, v155
	v_cvt_pk_bf16_f32 v161, v152, v153
	v_cvt_pk_bf16_f32 v162, v150, v151
	v_mfma_f32_32x32x16_bf16 v[64:79], v[236:239], v[240:243], v[64:79]
	ds_read_b128 v[236:239], v188 offset:36864
	ds_read_b128 v[240:243], v190 offset:49152
	v_cvt_pk_bf16_f32 v163, v148, v149
	v_add_f32_e32 v211, v211, v212
	v_cvt_pk_bf16_f32 v148, v225, v228
	v_cvt_pk_bf16_f32 v149, v226, v229
	v_cvt_pk_bf16_f32 v150, v227, v230
	v_cvt_pk_bf16_f32 v151, v223, v224
	s_waitcnt lgkmcnt(2)
	v_mfma_f32_32x32x16_bf16 v[80:95], v[248:251], v[232:235], v[80:95]
	ds_read_b128 v[248:251], v177
	v_cvt_pk_bf16_f32 v152, v219, v221
	v_cvt_pk_bf16_f32 v153, v220, v222
	v_cvt_pk_bf16_f32 v154, v215, v217
	v_cvt_pk_bf16_f32 v155, v216, v218
	v_fma_f32 v176, v209, v176, v211
	v_mfma_f32_32x32x16_bf16 v[64:79], v[244:247], v[232:235], v[64:79]
	s_waitcnt lgkmcnt(0)
	v_mfma_f32_32x32x16_bf16 v[80:95], v[236:239], v[248:251], v[80:95]
	v_mfma_f32_32x32x16_bf16 v[64:79], v[240:243], v[248:251], v[64:79]
	s_lshl_b32 s31, s30, 14
	v_add_u32_e32 v180, s31, v178
	ds_read_b64_tr_b16 v[232:233], v180 offset:0
	ds_read_b64_tr_b16 v[234:235], v180 offset:2048
	ds_read_b64_tr_b16 v[236:237], v180 offset:512
	ds_read_b64_tr_b16 v[238:239], v180 offset:2560
	ds_read_b64_tr_b16 v[240:241], v180 offset:1024
	ds_read_b64_tr_b16 v[242:243], v180 offset:3072
	ds_read_b64_tr_b16 v[248:249], v180 offset:1536
	ds_read_b64_tr_b16 v[250:251], v180 offset:3584
	ds_read_b64_tr_b16 v[244:245], v180 offset:4096
	ds_read_b64_tr_b16 v[246:247], v180 offset:6144
	s_nop 3
	v_mul_f32_e32 v212, 0xbdd53b94, v210
	v_max3_f32 v194, v80, v81, v82
	v_fmamk_f32 v225, v80, 0x3dd53b94, v212
	v_max3_f32 v195, v64, v65, v66
	v_fmamk_f32 v228, v81, 0x3dd53b94, v212
	s_waitcnt lgkmcnt(6)
	v_mfma_f32_32x32x16_bf16 v[32:47], v[148:151], v[232:235], v[32:47]
	ds_read_b64_tr_b16 v[232:233], v180 offset:4608
	ds_read_b64_tr_b16 v[234:235], v180 offset:6656
	v_max3_f32 v194, v194, v83, v84
	v_fmamk_f32 v226, v82, 0x3dd53b94, v212
	v_max3_f32 v195, v195, v67, v68
	v_fmamk_f32 v229, v83, 0x3dd53b94, v212
	v_max3_f32 v194, v194, v85, v86
	v_mfma_f32_32x32x16_bf16 v[48:63], v[148:151], v[236:239], v[48:63]
	ds_read_b64_tr_b16 v[236:237], v180 offset:5120
	ds_read_b64_tr_b16 v[238:239], v180 offset:7168
	v_fmamk_f32 v227, v84, 0x3dd53b94, v212
	v_max3_f32 v195, v195, v69, v70
	v_fmamk_f32 v230, v85, 0x3dd53b94, v212
	v_max3_f32 v194, v194, v87, v88
	v_fmamk_f32 v223, v86, 0x3dd53b94, v212
	s_waitcnt lgkmcnt(6)
	v_mfma_f32_32x32x16_bf16 v[16:31], v[148:151], v[240:243], v[16:31]
	ds_read_b64_tr_b16 v[240:241], v180 offset:5632
	ds_read_b64_tr_b16 v[242:243], v180 offset:7680
	v_max3_f32 v195, v195, v71, v72
	v_fmamk_f32 v224, v87, 0x3dd53b94, v212
	v_max3_f32 v194, v194, v89, v90
	v_fmamk_f32 v219, v88, 0x3dd53b94, v212
	v_max3_f32 v195, v195, v73, v74
	v_mfma_f32_32x32x16_bf16 v[0:15], v[148:151], v[248:251], v[0:15]
	ds_read_b64_tr_b16 v[248:249], v180 offset:8192
	ds_read_b64_tr_b16 v[250:251], v180 offset:10240
	v_fmamk_f32 v221, v89, 0x3dd53b94, v212
	v_max3_f32 v194, v194, v91, v92
	v_fmamk_f32 v220, v90, 0x3dd53b94, v212
	v_max3_f32 v195, v195, v75, v76
	v_fmamk_f32 v222, v91, 0x3dd53b94, v212
	s_waitcnt lgkmcnt(6)
	v_mfma_f32_32x32x16_bf16 v[32:47], v[152:155], v[244:247], v[32:47]
	ds_read_b64_tr_b16 v[244:245], v180 offset:8704
	ds_read_b64_tr_b16 v[246:247], v180 offset:10752
	v_max3_f32 v194, v194, v93, v94
	v_fmamk_f32 v215, v92, 0x3dd53b94, v212
	v_max3_f32 v195, v195, v77, v78
	v_fmamk_f32 v217, v93, 0x3dd53b94, v212
	v_max3_f32 v194, v194, v95, v195
	v_mfma_f32_32x32x16_bf16 v[48:63], v[152:155], v[232:235], v[48:63]
	ds_read_b64_tr_b16 v[232:233], v180 offset:9216
	ds_read_b64_tr_b16 v[234:235], v180 offset:11264
	v_fmamk_f32 v216, v94, 0x3dd53b94, v212
	v_max_f32_e32 v194, v194, v79
	v_fmamk_f32 v218, v95, 0x3dd53b94, v212
	v_mov_b32_e32 v195, v194
	s_nop 1
	s_waitcnt lgkmcnt(6)
	v_mfma_f32_32x32x16_bf16 v[16:31], v[152:155], v[236:239], v[16:31]
	ds_read_b64_tr_b16 v[236:237], v180 offset:9728
	ds_read_b64_tr_b16 v[238:239], v180 offset:11776
	v_permlane32_swap_b32_e32 v194, v195
	v_max_f32_e32 v194, v194, v195
	v_sub_f32_e32 v195, v194, v210
	v_cmp_ge_f32_e32 vcc, s15, v195
	v_mfma_f32_32x32x16_bf16 v[0:15], v[152:155], v[240:243], v[0:15]
	ds_read_b64_tr_b16 v[240:241], v180 offset:12288
	ds_read_b64_tr_b16 v[242:243], v180 offset:14336
	s_cmp_eq_u64 vcc, exec
	s_cselect_b64 s[40:41], -1, 0
	s_cbranch_scc1 .Lattn_fast1
	v_max_f32_e32 v194, v210, v194
	v_sub_f32_e32 v195, v210, v194
	v_mul_f32_e32 v195, 0x3dd53b94, v195
	v_exp_f32_e32 v214, v195
	v_mov_b32_e32 v210, v194
	v_mul_f32_e32 v212, 0xbdd53b94, v194
	v_add_f32_e32 v225, v225, v195
	v_add_f32_e32 v228, v228, v195
	v_add_f32_e32 v226, v226, v195
	v_add_f32_e32 v229, v229, v195
	v_add_f32_e32 v227, v227, v195
	v_add_f32_e32 v230, v230, v195
	v_add_f32_e32 v223, v223, v195
	v_add_f32_e32 v224, v224, v195
	v_add_f32_e32 v219, v219, v195
	v_add_f32_e32 v221, v221, v195
	v_add_f32_e32 v220, v220, v195
	v_add_f32_e32 v222, v222, v195
	v_add_f32_e32 v215, v215, v195
	v_add_f32_e32 v217, v217, v195
	v_add_f32_e32 v216, v216, v195
	v_add_f32_e32 v218, v218, v195
	s_branch .Lattn_join1
